# v20 + first two vmcnt waits of the K-loop pass that follows a unit epilogue (P1, P7) no longer wait for the 16 epilogue store acks (in-order vmcnt): vmcnt(24)
# speedup vs baseline: 1.0009x; 1.0009x over previous
; #define PG8_STAGE(bufoff, gbase, voff) do { _Pragma("unroll") for (int _i = 0; _i < 2; ++_i) \
;         __builtin_amdgcn_global_load_lds((const unsigned*)((const char*)(gbase) + (voff)[_i]), (PG8_LAS unsigned*)(lds + (bufoff) + ldsw + _i * 8192), 16, 0, 0); } while (0)
; #define PG8_WAIT_V(n) asm volatile("s_waitcnt vmcnt(" #n ")" ::: "memory")
; #define PG8_BAR __builtin_amdgcn_s_barrier()
; template <class Epi, class Sched, bool ALIGN_EPI = false, bool SP2 = false>
; __device__ __forceinline__ void gemm_phase(PG8_LAS unsigned char* lds, const Gemm g, const Sched& S, const Epi& E) {
;     ...
;     const int tid = tid_, wid = __builtin_amdgcn_readfirstlane(tid >> 6), lane = tid & 63, wr = wid >> 2, wc = wid & 3, fr = lane & 15, fq = lane >> 4;
;     const int K = g.K, nt = K / BK;
;     unsigned voffA[2], voffB[2];
; #pragma unroll
;     for (int i = 0; i < 2; ++i) { int R, C; stage_rc(tid * 16 + i * 8192, R, C); const int Rb = CWS * (R >> 5) + (Epi::PERM ? perm32(R & 31) : (R & 31));
;         voffA[i] = (unsigned)(R * K + C) * 2u; voffB[i] = (unsigned)(Rb * K + C) * 2u; }
;     const size_t kstep = (size_t)(BK * 2);
;     const size_t hstep = (size_t)HALF * K * 2;
;     const size_t hstepB = (size_t)CBS * K * 2;
;     const size_t tstep = 2 * hstep;
;     const unsigned ldsw = (unsigned)wid * 1024u;
;     const int aoff = lds_byte(wr * 64 + fr, fq * 8), boff = lds_byte(wc * 32 + fr, fq * 8);
;     ...
;         PG8_WAIT_V(2); PG8_BAR;
;         PG8_STAGE(PG8_SB(1, 0), cB + kstep, voffB); PG8_STAGE(PG8_SA(1, 0), cA + kstep, voffA); PG8_STAGE(PG8_SB(1, 1), cB + hstepB + kstep, voffB);
;         PG8_WAIT_V(6); PG8_BAR;
.LBB0_186:
	s_mov_b64 s[6:7], 0x80
	s_and_b32 s3, s3, 3
	s_add_i32 m0, s27, 0x18000
	v_lshl_add_u64 v[8:9], v[8:9], 0, s[6:7]
	s_lshl_b32 s5, s8, 13
	s_lshl_b32 s9, s3, 12
	s_mov_b32 s101, 0
	s_waitcnt vmcnt(2)
	s_barrier
	global_load_lds_dwordx4 v[8:9], off
	v_lshl_add_u64 v[6:7], v[6:7], 0, s[6:7]
	s_add_i32 m0, s27, 0x1a000
	s_add_i32 s33, s27, 0x8000
	s_add_i32 s34, s27, 0xa000
	global_load_lds_dwordx4 v[6:7], off
	v_lshl_add_u64 v[2:3], v[2:3], 0, s[6:7]
	s_mov_b32 m0, s33
	s_add_u32 s10, s22, 0x10080
	global_load_lds_dwordx4 v[2:3], off
	v_lshl_add_u64 v[2:3], v[4:5], 0, s[6:7]
	s_mov_b32 m0, s34
	s_addc_u32 s11, s23, 0
	global_load_lds_dwordx4 v[2:3], off
	s_add_i32 m0, s27, 0x1c000
	v_lshl_add_u64 v[2:3], s[10:11], 0, v[132:133]
	global_load_lds_dwordx4 v[2:3], off
	v_lshl_add_u64 v[2:3], s[10:11], 0, v[136:137]
	s_add_i32 m0, s27, 0x1e000
	s_cmpk_lt_u32 s2, 0x100
	global_load_lds_dwordx4 v[2:3], off
	v_lshrrev_b32_e32 v3, 1, v10
	v_and_b32_e32 v3, 24, v3
	v_and_b32_e32 v2, 15, v10
	v_lshlrev_b32_e32 v4, 1, v3
	v_lshl_or_b32 v1, s8, 6, v2
	v_lshl_or_b32 v2, v2, 6, v4
	v_lshlrev_b32_e32 v4, 2, v10
	v_and_b32_e32 v4, 32, v4
	v_bitop3_b32 v5, v2, s5, v4 bitop3:0xde
	v_bitop3_b32 v150, v2, s9, v4 bitop3:0xde
	v_lshlrev_b32_e32 v2, 14, v11
	v_and_b32_e32 v2, 0xffff8000, v2
	v_lshl_or_b32 v151, s3, 6, v3
	v_lshl_add_u32 v2, v12, 11, v2
	v_and_b32_e32 v3, 1, v11
	v_lshl_or_b32 v2, v3, 6, v2
	v_lshl_add_u32 v138, v13, 1, v2
	v_lshlrev_b32_e32 v2, 14, v14
	v_and_b32_e32 v2, 0xffff8000, v2
	s_waitcnt vmcnt(6)
	v_lshl_add_u32 v2, v15, 11, v2
	v_and_b32_e32 v3, 1, v14
	s_cselect_b64 s[8:9], -1, 0
	v_lshl_or_b32 v2, v3, 6, v2
	s_add_i32 s69, 0, 0x10000
	s_add_i32 s70, 0, 0x14000
	s_ashr_i32 s35, s93, 31
	s_ashr_i32 s68, s96, 31
	v_mov_b32_e32 v139, v133
	v_lshl_add_u32 v140, v16, 1, v2
	v_mov_b32_e32 v141, v133
	v_mov_b64_e32 v[142:143], 0x4c0
	v_mov_b64_e32 v[144:145], 0x4bf
	v_add_u32_e32 v152, s69, v150
	v_add_u32_e32 v153, s70, v150
	v_add_u32_e32 v154, 0, v5
	s_movk_i32 s71, 0x2600
	s_movk_i32 s72, 0x1210
	s_barrier
	s_branch .LBB0_189

; #define PG8_STAGE(bufoff, gbase, voff) do { _Pragma("unroll") for (int _i = 0; _i < 2; ++_i) \
;         __builtin_amdgcn_global_load_lds((const unsigned*)((const char*)(gbase) + (voff)[_i]), (PG8_LAS unsigned*)(lds + (bufoff) + ldsw + _i * 8192), 16, 0, 0); } while (0)
; #define PG8_LDA(dst, b, h) do { _Pragma("unroll") for (int m = 0; m < 4; ++m) _Pragma("unroll") for (int k = 0; k < 2; ++k) dst[m][k] = *(const PG8_LAS bf16x8*)(lds + PG8_SA(b, h) + aoff + m * 2048 + k * 1024); } while (0)
; #define PG8_LDB(dst, b, h) do { _Pragma("unroll") for (int n = 0; n < 2; ++n) _Pragma("unroll") for (int k = 0; k < 2; ++k) dst[n][k] = *(const PG8_LAS bf16x8*)(lds + PG8_SB(b, h) + boff + n * 2048 + k * 1024); } while (0)
; #define PG8_MMA(ai, bj, At, Bt) do { __builtin_amdgcn_s_setprio(1); _Pragma("unroll") for (int m = 0; m < 4; ++m) _Pragma("unroll") for (int n = 0; n < 2; ++n) _Pragma("unroll") for (int k = 0; k < 2; ++k) \
;         acc[ai][bj][m][n] = __builtin_amdgcn_mfma_f32_16x16x32_bf16(Bt[n][k], At[m][k], acc[ai][bj][m][n], 0, 0, 0); __builtin_amdgcn_s_setprio(0); } while (0)
; #define PG8_WAIT_V(n) asm volatile("s_waitcnt vmcnt(" #n ")" ::: "memory")
; #define PG8_WAIT_L(n) asm volatile("s_waitcnt lgkmcnt(" #n ")" ::: "memory")
; #define PG8_BAR __builtin_amdgcn_s_barrier()
; #define PG8_SCHED __builtin_amdgcn_sched_barrier(0)
; template <class Epi, class Sched, bool ALIGN_EPI = false, bool SP2 = false>
; __device__ __forceinline__ void gemm_phase(PG8_LAS unsigned char* lds, const Gemm g, const Sched& S, const Epi& E) {
;     ...
;             const char* a1 = cA + (size_t)(t + 1) * kstep;
;             const char* a2 = last ? nA : cA + (size_t)(t + 2) * kstep; const char* b2 = last ? nB : cB + (size_t)(t + 2) * kstep;
;             const char* a3 = a2 + kstep; const char* b3 = b2 + kstep;
;             if (last && has_next) S.a_ready(nxt);
;             if constexpr (SP2) {
;             PG8_LDB(B0, 0, 0); PG8_LDB(B1, 0, 1); PG8_SCHED; PG8_LDA(At, 0, 0); PG8_STAGE(PG8_SA(1, 1), a1 + hstep, voffA);
;             PG8_WAIT_V(8); PG8_WAIT_L(0); PG8_BAR; PG8_MMA(0, 0, At, B0); PG8_MMA(0, 1, At, B1); PG8_BAR; PG8_SCHED;
;             PG8_LDA(At, 0, 1); PG8_STAGE(PG8_SB(0, 0), b2, voffB); PG8_STAGE(PG8_SB(0, 1), b2 + hstepB, voffB); PG8_STAGE(PG8_SA(0, 0), a2, voffA);
.LBB0_192:
	ds_read_b128 v[146:149], v152
	ds_read_b128 v[156:159], v152 offset:1024
	ds_read_b128 v[160:163], v152 offset:2048
	ds_read_b128 v[164:167], v152 offset:3072
	ds_read_b128 v[168:171], v153
	ds_read_b128 v[172:175], v153 offset:1024
	ds_read_b128 v[176:179], v153 offset:2048
	ds_read_b128 v[180:183], v153 offset:3072
	s_add_u32 s22, s20, 0xfffc0080
	s_addc_u32 s23, s21, -1
	s_cmp_eq_u32 s75, 12
	s_cselect_b32 s25, s5, s23
	s_cselect_b32 s24, s13, s22
	s_cselect_b32 s23, s11, s74
	s_cselect_b32 s22, s19, s73
	v_lshl_add_u64 v[216:217], s[20:21], 0, v[138:139]
	s_add_i32 m0, s27, 0xc000
	ds_read_b128 v[184:187], v154
	ds_read_b128 v[188:191], v154 offset:1024
	ds_read_b128 v[192:195], v154 offset:2048
	ds_read_b128 v[196:199], v154 offset:3072
	ds_read_b128 v[200:203], v154 offset:4096
	ds_read_b128 v[204:207], v154 offset:5120
	ds_read_b128 v[208:211], v154 offset:6144
	ds_read_b128 v[212:215], v154 offset:7168
	global_load_lds_dwordx4 v[216:217], off
	v_lshl_add_u64 v[216:217], s[20:21], 0, v[140:141]
	s_add_i32 m0, s27, 0xe000
	s_nop 0
	global_load_lds_dwordx4 v[216:217], off
	s_waitcnt vmcnt(24)
	s_waitcnt lgkmcnt(0)
	s_barrier
	v_mfma_f32_16x16x32_bf16 v[126:129], v[146:149], v[184:187], v[126:129]
	v_mfma_f32_16x16x32_bf16 v[122:125], v[160:163], v[184:187], v[122:125]
	v_mfma_f32_16x16x32_bf16 v[114:117], v[146:149], v[192:195], v[114:117]
	v_mfma_f32_16x16x32_bf16 v[106:109], v[160:163], v[192:195], v[106:109]
	v_mfma_f32_16x16x32_bf16 v[98:101], v[146:149], v[200:203], v[98:101]
	v_mfma_f32_16x16x32_bf16 v[90:93], v[160:163], v[200:203], v[90:93]
	v_mfma_f32_16x16x32_bf16 v[82:85], v[146:149], v[208:211], v[82:85]
	v_mfma_f32_16x16x32_bf16 v[74:77], v[160:163], v[208:211], v[74:77]
	v_mfma_f32_16x16x32_bf16 v[126:129], v[156:159], v[188:191], v[126:129]
	v_mfma_f32_16x16x32_bf16 v[122:125], v[164:167], v[188:191], v[122:125]
	v_mfma_f32_16x16x32_bf16 v[114:117], v[156:159], v[196:199], v[114:117]
	v_mfma_f32_16x16x32_bf16 v[106:109], v[164:167], v[196:199], v[106:109]
	v_mfma_f32_16x16x32_bf16 v[98:101], v[156:159], v[204:207], v[98:101]
	v_mfma_f32_16x16x32_bf16 v[90:93], v[164:167], v[204:207], v[90:93]
	v_mfma_f32_16x16x32_bf16 v[82:85], v[156:159], v[212:215], v[82:85]
	v_mfma_f32_16x16x32_bf16 v[74:77], v[164:167], v[212:215], v[74:77]
	v_mfma_f32_16x16x32_bf16 v[118:121], v[168:171], v[184:187], v[118:121]
	v_mfma_f32_16x16x32_bf16 v[110:113], v[176:179], v[184:187], v[110:113]
	v_mfma_f32_16x16x32_bf16 v[102:105], v[168:171], v[192:195], v[102:105]
	v_mfma_f32_16x16x32_bf16 v[94:97], v[176:179], v[192:195], v[94:97]
	v_mfma_f32_16x16x32_bf16 v[86:89], v[168:171], v[200:203], v[86:89]
	v_mfma_f32_16x16x32_bf16 v[78:81], v[176:179], v[200:203], v[78:81]
	v_mfma_f32_16x16x32_bf16 v[70:73], v[168:171], v[208:211], v[70:73]
	v_mfma_f32_16x16x32_bf16 v[66:69], v[176:179], v[208:211], v[66:69]
	v_mfma_f32_16x16x32_bf16 v[118:121], v[172:175], v[188:191], v[118:121]
	v_mfma_f32_16x16x32_bf16 v[110:113], v[180:183], v[188:191], v[110:113]
	v_mfma_f32_16x16x32_bf16 v[102:105], v[172:175], v[196:199], v[102:105]
	v_mfma_f32_16x16x32_bf16 v[94:97], v[180:183], v[196:199], v[94:97]
	v_mfma_f32_16x16x32_bf16 v[86:89], v[172:175], v[204:207], v[86:89]
	v_mfma_f32_16x16x32_bf16 v[78:81], v[180:183], v[204:207], v[78:81]
	v_mfma_f32_16x16x32_bf16 v[70:73], v[172:175], v[212:215], v[70:73]
	v_mfma_f32_16x16x32_bf16 v[66:69], v[180:183], v[212:215], v[66:69]
	s_barrier
	s_add_i32 s76, s69, s26
	v_lshl_add_u64 v[216:217], s[22:23], 0, v[132:133]
	s_mov_b32 m0, s76
	ds_read_b128 v[184:187], v154 offset:16384
	ds_read_b128 v[188:191], v154 offset:17408
	ds_read_b128 v[192:195], v154 offset:18432
	ds_read_b128 v[196:199], v154 offset:19456
	ds_read_b128 v[200:203], v154 offset:20480
	ds_read_b128 v[204:207], v154 offset:21504
	ds_read_b128 v[208:211], v154 offset:22528
	ds_read_b128 v[212:215], v154 offset:23552
	global_load_lds_dwordx4 v[216:217], off
	s_add_i32 m0, s76, 0x2000
	s_add_u32 s76, s22, 0x10000
	v_lshl_add_u64 v[218:219], s[22:23], 0, v[136:137]
	s_addc_u32 s77, s23, 0
	s_add_i32 s78, s70, s26
	global_load_lds_dwordx4 v[218:219], off
	v_lshl_add_u64 v[220:221], s[76:77], 0, v[132:133]
	s_mov_b32 m0, s78
	v_lshl_add_u64 v[222:223], s[24:25], 0, v[134:135]
	global_load_lds_dwordx4 v[220:221], off
	v_lshl_add_u64 v[220:221], s[76:77], 0, v[136:137]
	s_add_i32 m0, s78, 0x2000
	s_nop 0
	global_load_lds_dwordx4 v[220:221], off
	v_lshl_add_u64 v[220:221], s[24:25], 0, v[130:131]
	s_mov_b32 m0, s27
	s_nop 0
	global_load_lds_dwordx4 v[220:221], off
	s_mov_b32 m0, s28
	s_nop 0
	global_load_lds_dwordx4 v[222:223], off
	s_cmp_lg_u32 s101, 0
	s_cbranch_scc1 .Lrx1
	s_waitcnt vmcnt(8)
	s_branch .Lrj1
.Lrx1:
	s_waitcnt vmcnt(24)
	s_mov_b32 s101, 0
; #define PG8_STAGE(bufoff, gbase, voff) do { _Pragma("unroll") for (int _i = 0; _i < 2; ++_i) \
;         __builtin_amdgcn_global_load_lds((const unsigned*)((const char*)(gbase) + (voff)[_i]), (PG8_LAS unsigned*)(lds + (bufoff) + ldsw + _i * 8192), 16, 0, 0); } while (0)
; #define PG8_LDA(dst, b, h) do { _Pragma("unroll") for (int m = 0; m < 4; ++m) _Pragma("unroll") for (int k = 0; k < 2; ++k) dst[m][k] = *(const PG8_LAS bf16x8*)(lds + PG8_SA(b, h) + aoff + m * 2048 + k * 1024); } while (0)
; #define PG8_LDB(dst, b, h) do { _Pragma("unroll") for (int n = 0; n < 2; ++n) _Pragma("unroll") for (int k = 0; k < 2; ++k) dst[n][k] = *(const PG8_LAS bf16x8*)(lds + PG8_SB(b, h) + boff + n * 2048 + k * 1024); } while (0)
; #define PG8_MMA(ai, bj, At, Bt) do { __builtin_amdgcn_s_setprio(1); _Pragma("unroll") for (int m = 0; m < 4; ++m) _Pragma("unroll") for (int n = 0; n < 2; ++n) _Pragma("unroll") for (int k = 0; k < 2; ++k) \
;         acc[ai][bj][m][n] = __builtin_amdgcn_mfma_f32_16x16x32_bf16(Bt[n][k], At[m][k], acc[ai][bj][m][n], 0, 0, 0); __builtin_amdgcn_s_setprio(0); } while (0)
; #define PG8_WAIT_V(n) asm volatile("s_waitcnt vmcnt(" #n ")" ::: "memory")
; #define PG8_WAIT_L(n) asm volatile("s_waitcnt lgkmcnt(" #n ")" ::: "memory")
; #define PG8_BAR __builtin_amdgcn_s_barrier()
; #define PG8_SCHED __builtin_amdgcn_sched_barrier(0)
; template <class Epi, class Sched, bool ALIGN_EPI = false, bool SP2 = false>
; __device__ __forceinline__ void gemm_phase(PG8_LAS unsigned char* lds, const Gemm g, const Sched& S, const Epi& E) {
;     ...
;             PG8_WAIT_V(8); PG8_WAIT_L(0); PG8_BAR; PG8_MMA(1, 0, At, B0); PG8_MMA(1, 1, At, B1); PG8_BAR; PG8_SCHED;
;             PG8_LDB(B0, 1, 0); PG8_LDB(B1, 1, 1); PG8_SCHED; PG8_LDA(At, 1, 0); PG8_STAGE(PG8_SA(0, 1), a2 + hstep, voffA);
;             PG8_WAIT_V(8); PG8_WAIT_L(0); PG8_BAR; PG8_MMA(0, 0, At, B0); PG8_MMA(0, 1, At, B1); PG8_BAR; PG8_SCHED;
.Lrj1:
	s_waitcnt lgkmcnt(0)
	s_barrier
	v_mfma_f32_16x16x32_bf16 v[62:65], v[146:149], v[184:187], v[62:65]
	v_mfma_f32_16x16x32_bf16 v[58:61], v[160:163], v[184:187], v[58:61]
	v_mfma_f32_16x16x32_bf16 v[50:53], v[146:149], v[192:195], v[50:53]
	v_mfma_f32_16x16x32_bf16 v[42:45], v[160:163], v[192:195], v[42:45]
	v_mfma_f32_16x16x32_bf16 v[34:37], v[146:149], v[200:203], v[34:37]
	v_mfma_f32_16x16x32_bf16 v[26:29], v[160:163], v[200:203], v[26:29]
	v_mfma_f32_16x16x32_bf16 v[18:21], v[146:149], v[208:211], v[18:21]
	v_mfma_f32_16x16x32_bf16 v[10:13], v[160:163], v[208:211], v[10:13]
	v_mfma_f32_16x16x32_bf16 v[62:65], v[156:159], v[188:191], v[62:65]
	v_mfma_f32_16x16x32_bf16 v[58:61], v[164:167], v[188:191], v[58:61]
	v_mfma_f32_16x16x32_bf16 v[50:53], v[156:159], v[196:199], v[50:53]
	v_mfma_f32_16x16x32_bf16 v[42:45], v[164:167], v[196:199], v[42:45]
	v_mfma_f32_16x16x32_bf16 v[34:37], v[156:159], v[204:207], v[34:37]
	v_mfma_f32_16x16x32_bf16 v[26:29], v[164:167], v[204:207], v[26:29]
	v_mfma_f32_16x16x32_bf16 v[18:21], v[156:159], v[212:215], v[18:21]
	v_mfma_f32_16x16x32_bf16 v[10:13], v[164:167], v[212:215], v[10:13]
	v_mfma_f32_16x16x32_bf16 v[54:57], v[168:171], v[184:187], v[54:57]
	v_mfma_f32_16x16x32_bf16 v[46:49], v[176:179], v[184:187], v[46:49]
	v_mfma_f32_16x16x32_bf16 v[38:41], v[168:171], v[192:195], v[38:41]
	v_mfma_f32_16x16x32_bf16 v[30:33], v[176:179], v[192:195], v[30:33]
	v_mfma_f32_16x16x32_bf16 v[22:25], v[168:171], v[200:203], v[22:25]
	v_mfma_f32_16x16x32_bf16 v[14:17], v[176:179], v[200:203], v[14:17]
	v_mfma_f32_16x16x32_bf16 v[6:9], v[168:171], v[208:211], v[6:9]
	v_mfma_f32_16x16x32_bf16 v[2:5], v[176:179], v[208:211], v[2:5]
	v_mfma_f32_16x16x32_bf16 v[54:57], v[172:175], v[188:191], v[54:57]
	v_mfma_f32_16x16x32_bf16 v[46:49], v[180:183], v[188:191], v[46:49]
	v_mfma_f32_16x16x32_bf16 v[38:41], v[172:175], v[196:199], v[38:41]
	v_mfma_f32_16x16x32_bf16 v[30:33], v[180:183], v[196:199], v[30:33]
	v_mfma_f32_16x16x32_bf16 v[22:25], v[172:175], v[204:207], v[22:25]
	v_mfma_f32_16x16x32_bf16 v[14:17], v[180:183], v[204:207], v[14:17]
	v_mfma_f32_16x16x32_bf16 v[6:9], v[172:175], v[212:215], v[6:9]
	v_mfma_f32_16x16x32_bf16 v[2:5], v[180:183], v[212:215], v[2:5]
	s_barrier
	s_add_i32 s76, 0, 0x18000
	v_add_u32_e32 v155, s76, v150
	s_add_i32 s77, 0, 0x1c000
	ds_read_b128 v[146:149], v155
	ds_read_b128 v[156:159], v155 offset:1024
	ds_read_b128 v[160:163], v155 offset:2048
	ds_read_b128 v[164:167], v155 offset:3072
	v_add_u32_e32 v155, s77, v150
	ds_read_b128 v[168:171], v155
	ds_read_b128 v[172:175], v155 offset:1024
	ds_read_b128 v[176:179], v155 offset:2048
	ds_read_b128 v[180:183], v155 offset:3072
	s_add_u32 s24, s24, 0x40000
	s_addc_u32 s25, s25, 0
	s_mov_b32 m0, s29
	v_lshl_add_u64 v[224:225], s[24:25], 0, v[130:131]
	ds_read_b128 v[184:187], v154 offset:32768
	ds_read_b128 v[188:191], v154 offset:33792
	ds_read_b128 v[192:195], v154 offset:34816
	ds_read_b128 v[196:199], v154 offset:35840
	ds_read_b128 v[200:203], v154 offset:36864
	ds_read_b128 v[204:207], v154 offset:37888
	ds_read_b128 v[208:211], v154 offset:38912
	ds_read_b128 v[212:215], v154 offset:39936
	global_load_lds_dwordx4 v[224:225], off
	v_lshl_add_u64 v[224:225], s[24:25], 0, v[134:135]
	s_mov_b32 m0, s30
	s_nop 0
	global_load_lds_dwordx4 v[224:225], off
	s_waitcnt vmcnt(8)
	s_waitcnt lgkmcnt(0)
	s_barrier
	v_mfma_f32_16x16x32_bf16 v[126:129], v[146:149], v[184:187], v[126:129]
	v_mfma_f32_16x16x32_bf16 v[122:125], v[160:163], v[184:187], v[122:125]
	v_mfma_f32_16x16x32_bf16 v[114:117], v[146:149], v[192:195], v[114:117]
	v_mfma_f32_16x16x32_bf16 v[106:109], v[160:163], v[192:195], v[106:109]
	v_mfma_f32_16x16x32_bf16 v[98:101], v[146:149], v[200:203], v[98:101]
	v_mfma_f32_16x16x32_bf16 v[90:93], v[160:163], v[200:203], v[90:93]
	v_mfma_f32_16x16x32_bf16 v[82:85], v[146:149], v[208:211], v[82:85]
	v_mfma_f32_16x16x32_bf16 v[74:77], v[160:163], v[208:211], v[74:77]
	v_mfma_f32_16x16x32_bf16 v[126:129], v[156:159], v[188:191], v[126:129]
	v_mfma_f32_16x16x32_bf16 v[122:125], v[164:167], v[188:191], v[122:125]
	v_mfma_f32_16x16x32_bf16 v[114:117], v[156:159], v[196:199], v[114:117]
	v_mfma_f32_16x16x32_bf16 v[106:109], v[164:167], v[196:199], v[106:109]
	v_mfma_f32_16x16x32_bf16 v[98:101], v[156:159], v[204:207], v[98:101]
	v_mfma_f32_16x16x32_bf16 v[90:93], v[164:167], v[204:207], v[90:93]
	v_mfma_f32_16x16x32_bf16 v[82:85], v[156:159], v[212:215], v[82:85]
	v_mfma_f32_16x16x32_bf16 v[74:77], v[164:167], v[212:215], v[74:77]
	v_mfma_f32_16x16x32_bf16 v[118:121], v[168:171], v[184:187], v[118:121]
	v_mfma_f32_16x16x32_bf16 v[110:113], v[176:179], v[184:187], v[110:113]
	v_mfma_f32_16x16x32_bf16 v[102:105], v[168:171], v[192:195], v[102:105]
	v_mfma_f32_16x16x32_bf16 v[94:97], v[176:179], v[192:195], v[94:97]
	v_mfma_f32_16x16x32_bf16 v[86:89], v[168:171], v[200:203], v[86:89]
	v_mfma_f32_16x16x32_bf16 v[78:81], v[176:179], v[200:203], v[78:81]
	v_mfma_f32_16x16x32_bf16 v[70:73], v[168:171], v[208:211], v[70:73]
	v_mfma_f32_16x16x32_bf16 v[66:69], v[176:179], v[208:211], v[66:69]
	v_mfma_f32_16x16x32_bf16 v[118:121], v[172:175], v[188:191], v[118:121]
	v_mfma_f32_16x16x32_bf16 v[110:113], v[180:183], v[188:191], v[110:113]
	v_mfma_f32_16x16x32_bf16 v[102:105], v[172:175], v[196:199], v[102:105]
	v_mfma_f32_16x16x32_bf16 v[94:97], v[180:183], v[196:199], v[94:97]
	v_mfma_f32_16x16x32_bf16 v[86:89], v[172:175], v[204:207], v[86:89]
	v_mfma_f32_16x16x32_bf16 v[78:81], v[180:183], v[204:207], v[78:81]
	v_mfma_f32_16x16x32_bf16 v[70:73], v[172:175], v[212:215], v[70:73]
	v_mfma_f32_16x16x32_bf16 v[66:69], v[180:183], v[212:215], v[66:69]
	s_barrier
; #define PG8_BAR __builtin_amdgcn_s_barrier()
;     __device__ __forceinline__ void operator()(const f32x4 (&acc)[2][2][4][2], const Unit& u, int wr, int wc, int fr, int fq) const {
;     ...
;             for (int m = 0; m < 4; ++m) { bf16_t* rowp = O + (size_t)(row0 + ai * HALF + m * 16) * ldc + col0;
; #pragma unroll
;                 for (int bj = 0; bj < 2; ++bj) { f32x4 v0 = acc[ai][bj][m][0], v1 = acc[ai][bj][m][1];
;                     if (ROWSCALE) { v0 = v0 * rs[ai][m]; v1 = v1 * rs[ai][m]; }
;                     if (ACT == 2) {
; #pragma unroll
; template <class Epi, class Sched, bool ALIGN_EPI = false, bool SP2 = false>
; __device__ __forceinline__ void gemm_phase(PG8_LAS unsigned char* lds, const Gemm g, const Sched& S, const Epi& E) {
;     ...
;             PG8_LDA(At, 1, 1); PG8_STAGE(PG8_SB(1, 0), b3, voffB); PG8_STAGE(PG8_SB(1, 1), b3 + hstepB, voffB); PG8_STAGE(PG8_SA(1, 0), a3, voffA);
;             PG8_WAIT_V(8); PG8_WAIT_L(0); PG8_BAR; PG8_MMA(1, 0, At, B0); PG8_MMA(1, 1, At, B1); PG8_BAR; PG8_SCHED;
;             } else {
;             PG8_LDB(B0, 0, 0); PG8_SCHED; PG8_LDA(At, 0, 0); PG8_STAGE(PG8_SA(1, 1), a1 + hstep, voffA);
;             PG8_WAIT_L(8); PG8_BAR; PG8_WAIT_L(0); PG8_MMA(0, 0, At, B0); PG8_BAR; PG8_SCHED;
;             PG8_LDB(B1, 0, 1); PG8_STAGE(PG8_SB(0, 0), b2, voffB);
;             PG8_BAR; PG8_WAIT_L(0); PG8_MMA(0, 1, At, B1); PG8_BAR;
;             PG8_LDA(At, 0, 1); PG8_STAGE(PG8_SA(0, 0), a2, voffA);
;             PG8_BAR; PG8_WAIT_L(0); PG8_MMA(1, 0, At, B0); PG8_BAR; PG8_SCHED;
;             PG8_STAGE(PG8_SB(0, 1), b2 + hstepB, voffB);
;             PG8_WAIT_V(6); PG8_BAR; PG8_MMA(1, 1, At, B1); PG8_BAR;
;             PG8_LDB(B0, 1, 0); PG8_SCHED; PG8_LDA(At, 1, 0); PG8_STAGE(PG8_SA(0, 1), a2 + hstep, voffA);
;             PG8_WAIT_L(8); PG8_BAR; PG8_WAIT_L(0); PG8_MMA(0, 0, At, B0); PG8_BAR; PG8_SCHED;
;             PG8_LDB(B1, 1, 1); PG8_STAGE(PG8_SB(1, 0), b3, voffB);
;             PG8_BAR; PG8_WAIT_L(0); PG8_MMA(0, 1, At, B1); PG8_BAR;
;             PG8_LDA(At, 1, 1); PG8_STAGE(PG8_SA(1, 0), a3, voffA);
;             PG8_BAR; PG8_WAIT_L(0); PG8_MMA(1, 0, At, B0); PG8_BAR; PG8_SCHED;
;             PG8_STAGE(PG8_SB(1, 1), b3 + hstepB, voffB);
;             PG8_WAIT_V(6); PG8_BAR; PG8_MMA(1, 1, At, B1); PG8_BAR;
;             }
;         }
;         if constexpr (ALIGN_EPI) { if (wr == 0) PG8_BAR; }
	s_add_i32 s24, s76, s26
	v_lshl_add_u64 v[216:217], v[216:217], 0, s[6:7]
	s_mov_b32 m0, s24
	ds_read_b128 v[184:187], v154 offset:49152
	ds_read_b128 v[188:191], v154 offset:50176
	ds_read_b128 v[192:195], v154 offset:51200
	ds_read_b128 v[196:199], v154 offset:52224
	ds_read_b128 v[200:203], v154 offset:53248
	ds_read_b128 v[204:207], v154 offset:54272
	ds_read_b128 v[208:211], v154 offset:55296
	ds_read_b128 v[212:215], v154 offset:56320
	global_load_lds_dwordx4 v[216:217], off
	s_add_i32 m0, s24, 0x2000
	s_add_u32 s22, s22, 0x10080
	v_lshl_add_u64 v[216:217], v[218:219], 0, s[6:7]
	s_addc_u32 s23, s23, 0
	s_add_i32 s24, s77, s26
	global_load_lds_dwordx4 v[216:217], off
	v_lshl_add_u64 v[216:217], s[22:23], 0, v[132:133]
	s_mov_b32 m0, s24
	s_nop 0
	global_load_lds_dwordx4 v[216:217], off
	v_lshl_add_u64 v[216:217], s[22:23], 0, v[136:137]
	s_add_i32 m0, s24, 0x2000
	s_nop 0
	global_load_lds_dwordx4 v[216:217], off
	v_lshl_add_u64 v[216:217], v[220:221], 0, s[6:7]
	s_mov_b32 m0, s33
	s_nop 0
	global_load_lds_dwordx4 v[216:217], off
	v_lshl_add_u64 v[216:217], v[222:223], 0, s[6:7]
	s_mov_b32 m0, s34
	s_nop 0
	global_load_lds_dwordx4 v[216:217], off
	s_waitcnt vmcnt(8)
	s_waitcnt lgkmcnt(0)
	s_barrier
	v_mfma_f32_16x16x32_bf16 v[62:65], v[146:149], v[184:187], v[62:65]
	v_mfma_f32_16x16x32_bf16 v[58:61], v[160:163], v[184:187], v[58:61]
	v_mfma_f32_16x16x32_bf16 v[50:53], v[146:149], v[192:195], v[50:53]
	v_mfma_f32_16x16x32_bf16 v[42:45], v[160:163], v[192:195], v[42:45]
	v_mfma_f32_16x16x32_bf16 v[34:37], v[146:149], v[200:203], v[34:37]
	v_mfma_f32_16x16x32_bf16 v[26:29], v[160:163], v[200:203], v[26:29]
	v_mfma_f32_16x16x32_bf16 v[18:21], v[146:149], v[208:211], v[18:21]
	v_mfma_f32_16x16x32_bf16 v[10:13], v[160:163], v[208:211], v[10:13]
	v_mfma_f32_16x16x32_bf16 v[62:65], v[156:159], v[188:191], v[62:65]
	v_mfma_f32_16x16x32_bf16 v[58:61], v[164:167], v[188:191], v[58:61]
	v_mfma_f32_16x16x32_bf16 v[50:53], v[156:159], v[196:199], v[50:53]
	v_mfma_f32_16x16x32_bf16 v[42:45], v[164:167], v[196:199], v[42:45]
	v_mfma_f32_16x16x32_bf16 v[34:37], v[156:159], v[204:207], v[34:37]
	v_mfma_f32_16x16x32_bf16 v[26:29], v[164:167], v[204:207], v[26:29]
	v_mfma_f32_16x16x32_bf16 v[18:21], v[156:159], v[212:215], v[18:21]
	v_mfma_f32_16x16x32_bf16 v[10:13], v[164:167], v[212:215], v[10:13]
	v_mfma_f32_16x16x32_bf16 v[54:57], v[168:171], v[184:187], v[54:57]
	v_mfma_f32_16x16x32_bf16 v[46:49], v[176:179], v[184:187], v[46:49]
	v_mfma_f32_16x16x32_bf16 v[38:41], v[168:171], v[192:195], v[38:41]
	v_mfma_f32_16x16x32_bf16 v[30:33], v[176:179], v[192:195], v[30:33]
	v_mfma_f32_16x16x32_bf16 v[22:25], v[168:171], v[200:203], v[22:25]
	v_mfma_f32_16x16x32_bf16 v[14:17], v[176:179], v[200:203], v[14:17]
	v_mfma_f32_16x16x32_bf16 v[6:9], v[168:171], v[208:211], v[6:9]
	v_mfma_f32_16x16x32_bf16 v[2:5], v[176:179], v[208:211], v[2:5]
	v_mfma_f32_16x16x32_bf16 v[54:57], v[172:175], v[188:191], v[54:57]
	v_mfma_f32_16x16x32_bf16 v[46:49], v[180:183], v[188:191], v[46:49]
	v_mfma_f32_16x16x32_bf16 v[38:41], v[172:175], v[196:199], v[38:41]
	v_mfma_f32_16x16x32_bf16 v[30:33], v[180:183], v[196:199], v[30:33]
	v_mfma_f32_16x16x32_bf16 v[22:25], v[172:175], v[204:207], v[22:25]
	v_mfma_f32_16x16x32_bf16 v[14:17], v[180:183], v[204:207], v[14:17]
	v_mfma_f32_16x16x32_bf16 v[6:9], v[172:175], v[212:215], v[6:9]
	v_mfma_f32_16x16x32_bf16 v[2:5], v[180:183], v[212:215], v[2:5]
	s_barrier
	s_add_i32 s75, s75, 2
	s_add_u32 s20, s20, 0x100
	s_addc_u32 s21, s21, 0
	s_add_u32 s73, s73, 0x100
	s_addc_u32 s74, s74, 0
	s_cmp_gt_u32 s75, 13
	s_cbranch_scc0 .LBB0_192
	s_and_b64 vcc, exec, s[8:9]
	s_cbranch_vccz .LBB0_195
	s_barrier
.LBB0_195:
	s_mov_b32 s101, 1
	v_lshl_add_u32 v155, s18, 8, v1
	v_lshl_or_b32 v146, s4, 8, v151
	v_mov_b64_e32 v[148:149], s[52:53]
	v_ashrrev_i32_e32 v147, 31, v146
	v_mad_i64_i32 v[148:149], s[4:5], v155, s71, v[148:149]
	v_lshl_add_u64 v[148:149], v[146:147], 1, v[148:149]
	v_cmp_gt_i32_e32 vcc, s72, v146
	v_cvt_pk_bf16_f32 v126, v126, v127
	v_cvt_pk_bf16_f32 v127, v128, v129
	v_cvt_pk_bf16_f32 v128, v122, v123
	v_cvt_pk_bf16_f32 v129, v124, v125
	s_and_saveexec_b64 s[4:5], vcc
	s_cbranch_execz .LBB0_197
	global_store_dwordx4 v[148:149], v[126:129], off

; #define PG8_STAGE(bufoff, gbase, voff) do { _Pragma("unroll") for (int _i = 0; _i < 2; ++_i) \
;         __builtin_amdgcn_global_load_lds((const unsigned*)((const char*)(gbase) + (voff)[_i]), (PG8_LAS unsigned*)(lds + (bufoff) + ldsw + _i * 8192), 16, 0, 0); } while (0)
; #define PG8_WAIT_V(n) asm volatile("s_waitcnt vmcnt(" #n ")" ::: "memory")
; #define PG8_BAR __builtin_amdgcn_s_barrier()
; template <class Epi, class Sched, bool ALIGN_EPI = false, bool SP2 = false>
; __device__ __forceinline__ void gemm_phase(PG8_LAS unsigned char* lds, const Gemm g, const Sched& S, const Epi& E) {
;     ...
;     const int tid = tid_, wid = __builtin_amdgcn_readfirstlane(tid >> 6), lane = tid & 63, wr = wid >> 2, wc = wid & 3, fr = lane & 15, fq = lane >> 4;
;     const int K = g.K, nt = K / BK;
;     unsigned voffA[2], voffB[2];
; #pragma unroll
;     for (int i = 0; i < 2; ++i) { int R, C; stage_rc(tid * 16 + i * 8192, R, C); const int Rb = CWS * (R >> 5) + (Epi::PERM ? perm32(R & 31) : (R & 31));
;         voffA[i] = (unsigned)(R * K + C) * 2u; voffB[i] = (unsigned)(Rb * K + C) * 2u; }
;     const size_t kstep = (size_t)(BK * 2);
;     const size_t hstep = (size_t)HALF * K * 2;
;     const size_t hstepB = (size_t)CBS * K * 2;
;     const size_t tstep = 2 * hstep;
;     const unsigned ldsw = (unsigned)wid * 1024u;
;     const int aoff = lds_byte(wr * 64 + fr, fq * 8), boff = lds_byte(wc * 32 + fr, fq * 8);
;     ...
;         PG8_WAIT_V(2); PG8_BAR;
;         PG8_STAGE(PG8_SB(1, 0), cB + kstep, voffB); PG8_STAGE(PG8_SA(1, 0), cA + kstep, voffA); PG8_STAGE(PG8_SB(1, 1), cB + hstepB + kstep, voffB);
;         PG8_WAIT_V(6); PG8_BAR;
.LBB0_1303:
	s_mov_b64 s[10:11], 0x80
	s_and_b32 s6, s6, 3
	s_add_i32 m0, s31, 0x18000
	v_lshl_add_u64 v[8:9], v[8:9], 0, s[10:11]
	s_lshl_b32 s9, s7, 13
	s_lshl_b32 s15, s6, 12
	s_mov_b32 s101, 0
	s_waitcnt vmcnt(2)
	s_barrier
	global_load_lds_dwordx4 v[8:9], off
	v_lshl_add_u64 v[6:7], v[6:7], 0, s[10:11]
	s_add_i32 m0, s31, 0x1a000
	s_add_i32 s47, s31, 0x8000
	s_add_i32 s54, s31, 0xa000
	global_load_lds_dwordx4 v[6:7], off
	v_lshl_add_u64 v[2:3], v[2:3], 0, s[10:11]
	s_mov_b32 m0, s47
	s_add_u32 s16, s40, 0x10080
	global_load_lds_dwordx4 v[2:3], off
	v_lshl_add_u64 v[2:3], v[4:5], 0, s[10:11]
	s_mov_b32 m0, s54
	s_addc_u32 s17, s41, 0
	global_load_lds_dwordx4 v[2:3], off
	s_add_i32 m0, s31, 0x1c000
	v_lshl_add_u64 v[2:3], s[16:17], 0, v[132:133]
	global_load_lds_dwordx4 v[2:3], off
	v_lshl_add_u64 v[2:3], s[16:17], 0, v[136:137]
	s_add_i32 m0, s31, 0x1e000
	s_cmpk_lt_u32 s14, 0x100
	global_load_lds_dwordx4 v[2:3], off
	v_lshrrev_b32_e32 v3, 1, v10
	v_and_b32_e32 v3, 24, v3
	v_and_b32_e32 v2, 15, v10
	v_lshlrev_b32_e32 v4, 1, v3
	v_lshl_or_b32 v1, s7, 6, v2
	v_lshl_or_b32 v2, v2, 6, v4
	v_lshlrev_b32_e32 v4, 2, v10
	v_and_b32_e32 v4, 32, v4
	v_bitop3_b32 v5, v2, s9, v4 bitop3:0xde
	v_bitop3_b32 v152, v2, s15, v4 bitop3:0xde
	v_lshlrev_b32_e32 v2, 14, v11
	v_and_b32_e32 v2, 0xffff8000, v2
	v_lshl_or_b32 v153, s6, 6, v3
	v_lshl_add_u32 v2, v12, 11, v2
	v_and_b32_e32 v3, 1, v11
	v_lshl_or_b32 v2, v3, 6, v2
	v_lshl_add_u32 v138, v13, 1, v2
	v_lshlrev_b32_e32 v2, 14, v14
	v_and_b32_e32 v2, 0xffff8000, v2
	s_waitcnt vmcnt(6)
	v_lshl_add_u32 v2, v15, 11, v2
	v_and_b32_e32 v3, 1, v14
	s_cselect_b64 s[14:15], -1, 0
	v_lshl_or_b32 v2, v3, 6, v2
	s_add_i32 s57, 0, 0x10000
	s_add_i32 s58, 0, 0x14000
	s_ashr_i32 s55, s76, 31
	s_ashr_i32 s56, s66, 31
	v_mov_b32_e32 v139, v133
	v_lshl_add_u32 v140, v16, 1, v2
	v_mov_b32_e32 v141, v133
	v_mov_b64_e32 v[142:143], 0x400
	v_mov_b64_e32 v[144:145], 0x3ff
	v_add_u32_e32 v154, s57, v152
	v_add_u32_e32 v155, s58, v152
	v_add_u32_e32 v156, 0, v5
	s_mov_b64 s[16:17], 0x100000
	s_mov_b64 s[18:19], 0x120000
	s_mov_b64 s[20:21], 0x140000
	s_mov_b64 s[22:23], 0x160000
	s_barrier
	s_waitcnt vmcnt(0)
	s_branch .LBB0_1306

; #define PG8_STAGE(bufoff, gbase, voff) do { _Pragma("unroll") for (int _i = 0; _i < 2; ++_i) \
;         __builtin_amdgcn_global_load_lds((const unsigned*)((const char*)(gbase) + (voff)[_i]), (PG8_LAS unsigned*)(lds + (bufoff) + ldsw + _i * 8192), 16, 0, 0); } while (0)
; #define PG8_LDA(dst, b, h) do { _Pragma("unroll") for (int m = 0; m < 4; ++m) _Pragma("unroll") for (int k = 0; k < 2; ++k) dst[m][k] = *(const PG8_LAS bf16x8*)(lds + PG8_SA(b, h) + aoff + m * 2048 + k * 1024); } while (0)
; #define PG8_LDB(dst, b, h) do { _Pragma("unroll") for (int n = 0; n < 2; ++n) _Pragma("unroll") for (int k = 0; k < 2; ++k) dst[n][k] = *(const PG8_LAS bf16x8*)(lds + PG8_SB(b, h) + boff + n * 2048 + k * 1024); } while (0)
; #define PG8_MMA(ai, bj, At, Bt) do { __builtin_amdgcn_s_setprio(1); _Pragma("unroll") for (int m = 0; m < 4; ++m) _Pragma("unroll") for (int n = 0; n < 2; ++n) _Pragma("unroll") for (int k = 0; k < 2; ++k) \
;         acc[ai][bj][m][n] = __builtin_amdgcn_mfma_f32_16x16x32_bf16(Bt[n][k], At[m][k], acc[ai][bj][m][n], 0, 0, 0); __builtin_amdgcn_s_setprio(0); } while (0)
; #define PG8_WAIT_V(n) asm volatile("s_waitcnt vmcnt(" #n ")" ::: "memory")
; #define PG8_WAIT_L(n) asm volatile("s_waitcnt lgkmcnt(" #n ")" ::: "memory")
; #define PG8_BAR __builtin_amdgcn_s_barrier()
; #define PG8_SCHED __builtin_amdgcn_sched_barrier(0)
; template <class Epi, class Sched, bool ALIGN_EPI = false, bool SP2 = false>
; __device__ __forceinline__ void gemm_phase(PG8_LAS unsigned char* lds, const Gemm g, const Sched& S, const Epi& E) {
;     ...
;             const char* a1 = cA + (size_t)(t + 1) * kstep;
;             const char* a2 = last ? nA : cA + (size_t)(t + 2) * kstep; const char* b2 = last ? nB : cB + (size_t)(t + 2) * kstep;
;             const char* a3 = a2 + kstep; const char* b3 = b2 + kstep;
;             if (last && has_next) S.a_ready(nxt);
;             if constexpr (SP2) {
;             PG8_LDB(B0, 0, 0); PG8_LDB(B1, 0, 1); PG8_SCHED; PG8_LDA(At, 0, 0); PG8_STAGE(PG8_SA(1, 1), a1 + hstep, voffA);
;             PG8_WAIT_V(8); PG8_WAIT_L(0); PG8_BAR; PG8_MMA(0, 0, At, B0); PG8_MMA(0, 1, At, B1); PG8_BAR; PG8_SCHED;
;             PG8_LDA(At, 0, 1); PG8_STAGE(PG8_SB(0, 0), b2, voffB); PG8_STAGE(PG8_SB(0, 1), b2 + hstepB, voffB); PG8_STAGE(PG8_SA(0, 0), a2, voffA);
.LBB0_1313:
	ds_read_b128 v[146:149], v154
	ds_read_b128 v[158:161], v154 offset:1024
	ds_read_b128 v[162:165], v154 offset:2048
	ds_read_b128 v[166:169], v154 offset:3072
	ds_read_b128 v[170:173], v155
	ds_read_b128 v[174:177], v155 offset:1024
	ds_read_b128 v[178:181], v155 offset:2048
	ds_read_b128 v[182:185], v155 offset:3072
	s_add_u32 s40, s38, 0xfffc0080
	s_addc_u32 s41, s39, -1
	s_cmp_eq_u32 s61, 12
	s_cselect_b32 s43, s9, s41
	s_cselect_b32 s42, s27, s40
	s_cselect_b32 s41, s25, s60
	s_cselect_b32 s40, s37, s59
	v_lshl_add_u64 v[150:151], s[38:39], 0, v[138:139]
	s_add_i32 m0, s31, 0xc000
	ds_read_b128 v[186:189], v156
	ds_read_b128 v[190:193], v156 offset:1024
	ds_read_b128 v[194:197], v156 offset:2048
	ds_read_b128 v[198:201], v156 offset:3072
	ds_read_b128 v[202:205], v156 offset:4096
	ds_read_b128 v[206:209], v156 offset:5120
	ds_read_b128 v[210:213], v156 offset:6144
	ds_read_b128 v[214:217], v156 offset:7168
	global_load_lds_dwordx4 v[150:151], off
	v_lshl_add_u64 v[150:151], s[38:39], 0, v[140:141]
	s_add_i32 m0, s31, 0xe000
	s_nop 0
	global_load_lds_dwordx4 v[150:151], off
	s_waitcnt vmcnt(24)
	s_waitcnt lgkmcnt(0)
	s_barrier
	v_mfma_f32_16x16x32_bf16 v[126:129], v[146:149], v[186:189], v[126:129]
	v_mfma_f32_16x16x32_bf16 v[122:125], v[162:165], v[186:189], v[122:125]
	v_mfma_f32_16x16x32_bf16 v[110:113], v[146:149], v[194:197], v[110:113]
	v_mfma_f32_16x16x32_bf16 v[106:109], v[162:165], v[194:197], v[106:109]
	v_mfma_f32_16x16x32_bf16 v[94:97], v[146:149], v[202:205], v[94:97]
	v_mfma_f32_16x16x32_bf16 v[90:93], v[162:165], v[202:205], v[90:93]
	v_mfma_f32_16x16x32_bf16 v[78:81], v[146:149], v[210:213], v[78:81]
	v_mfma_f32_16x16x32_bf16 v[74:77], v[162:165], v[210:213], v[74:77]
	v_mfma_f32_16x16x32_bf16 v[126:129], v[158:161], v[190:193], v[126:129]
	v_mfma_f32_16x16x32_bf16 v[122:125], v[166:169], v[190:193], v[122:125]
	v_mfma_f32_16x16x32_bf16 v[110:113], v[158:161], v[198:201], v[110:113]
	v_mfma_f32_16x16x32_bf16 v[106:109], v[166:169], v[198:201], v[106:109]
	v_mfma_f32_16x16x32_bf16 v[94:97], v[158:161], v[206:209], v[94:97]
	v_mfma_f32_16x16x32_bf16 v[90:93], v[166:169], v[206:209], v[90:93]
	v_mfma_f32_16x16x32_bf16 v[78:81], v[158:161], v[214:217], v[78:81]
	v_mfma_f32_16x16x32_bf16 v[74:77], v[166:169], v[214:217], v[74:77]
	v_mfma_f32_16x16x32_bf16 v[118:121], v[170:173], v[186:189], v[118:121]
	v_mfma_f32_16x16x32_bf16 v[114:117], v[178:181], v[186:189], v[114:117]
	v_mfma_f32_16x16x32_bf16 v[102:105], v[170:173], v[194:197], v[102:105]
	v_mfma_f32_16x16x32_bf16 v[98:101], v[178:181], v[194:197], v[98:101]
	v_mfma_f32_16x16x32_bf16 v[86:89], v[170:173], v[202:205], v[86:89]
	v_mfma_f32_16x16x32_bf16 v[82:85], v[178:181], v[202:205], v[82:85]
	v_mfma_f32_16x16x32_bf16 v[70:73], v[170:173], v[210:213], v[70:73]
	v_mfma_f32_16x16x32_bf16 v[66:69], v[178:181], v[210:213], v[66:69]
	v_mfma_f32_16x16x32_bf16 v[118:121], v[174:177], v[190:193], v[118:121]
	v_mfma_f32_16x16x32_bf16 v[114:117], v[182:185], v[190:193], v[114:117]
	v_mfma_f32_16x16x32_bf16 v[102:105], v[174:177], v[198:201], v[102:105]
	v_mfma_f32_16x16x32_bf16 v[98:101], v[182:185], v[198:201], v[98:101]
	v_mfma_f32_16x16x32_bf16 v[86:89], v[174:177], v[206:209], v[86:89]
	v_mfma_f32_16x16x32_bf16 v[82:85], v[182:185], v[206:209], v[82:85]
	v_mfma_f32_16x16x32_bf16 v[70:73], v[174:177], v[214:217], v[70:73]
	v_mfma_f32_16x16x32_bf16 v[66:69], v[182:185], v[214:217], v[66:69]
	s_barrier
	s_add_i32 s62, s57, s30
	v_lshl_add_u64 v[150:151], s[40:41], 0, v[132:133]
	s_mov_b32 m0, s62
	ds_read_b128 v[186:189], v156 offset:16384
	ds_read_b128 v[190:193], v156 offset:17408
	ds_read_b128 v[194:197], v156 offset:18432
	ds_read_b128 v[198:201], v156 offset:19456
	ds_read_b128 v[202:205], v156 offset:20480
	ds_read_b128 v[206:209], v156 offset:21504
	ds_read_b128 v[210:213], v156 offset:22528
	ds_read_b128 v[214:217], v156 offset:23552
	global_load_lds_dwordx4 v[150:151], off
	s_add_i32 m0, s62, 0x2000
	s_add_u32 s62, s40, 0x10000
	v_lshl_add_u64 v[218:219], s[40:41], 0, v[136:137]
	s_addc_u32 s63, s41, 0
	s_add_i32 s64, s58, s30
	global_load_lds_dwordx4 v[218:219], off
	v_lshl_add_u64 v[220:221], s[62:63], 0, v[132:133]
	s_mov_b32 m0, s64
	v_lshl_add_u64 v[222:223], s[42:43], 0, v[134:135]
	global_load_lds_dwordx4 v[220:221], off
	v_lshl_add_u64 v[220:221], s[62:63], 0, v[136:137]
	s_add_i32 m0, s64, 0x2000
	s_nop 0
	global_load_lds_dwordx4 v[220:221], off
	v_lshl_add_u64 v[220:221], s[42:43], 0, v[130:131]
	s_mov_b32 m0, s31
	s_nop 0
	global_load_lds_dwordx4 v[220:221], off
	s_mov_b32 m0, s33
	s_nop 0
	global_load_lds_dwordx4 v[222:223], off
	s_cmp_lg_u32 s101, 0
	s_cbranch_scc1 .Lrx7
	s_waitcnt vmcnt(8)
	s_branch .Lrj7

; #define PG8_STAGE(bufoff, gbase, voff) do { _Pragma("unroll") for (int _i = 0; _i < 2; ++_i) \
;         __builtin_amdgcn_global_load_lds((const unsigned*)((const char*)(gbase) + (voff)[_i]), (PG8_LAS unsigned*)(lds + (bufoff) + ldsw + _i * 8192), 16, 0, 0); } while (0)
; #define PG8_LDA(dst, b, h) do { _Pragma("unroll") for (int m = 0; m < 4; ++m) _Pragma("unroll") for (int k = 0; k < 2; ++k) dst[m][k] = *(const PG8_LAS bf16x8*)(lds + PG8_SA(b, h) + aoff + m * 2048 + k * 1024); } while (0)
; #define PG8_LDB(dst, b, h) do { _Pragma("unroll") for (int n = 0; n < 2; ++n) _Pragma("unroll") for (int k = 0; k < 2; ++k) dst[n][k] = *(const PG8_LAS bf16x8*)(lds + PG8_SB(b, h) + boff + n * 2048 + k * 1024); } while (0)
; #define PG8_MMA(ai, bj, At, Bt) do { __builtin_amdgcn_s_setprio(1); _Pragma("unroll") for (int m = 0; m < 4; ++m) _Pragma("unroll") for (int n = 0; n < 2; ++n) _Pragma("unroll") for (int k = 0; k < 2; ++k) \
;         acc[ai][bj][m][n] = __builtin_amdgcn_mfma_f32_16x16x32_bf16(Bt[n][k], At[m][k], acc[ai][bj][m][n], 0, 0, 0); __builtin_amdgcn_s_setprio(0); } while (0)
; #define PG8_WAIT_V(n) asm volatile("s_waitcnt vmcnt(" #n ")" ::: "memory")
; #define PG8_WAIT_L(n) asm volatile("s_waitcnt lgkmcnt(" #n ")" ::: "memory")
; #define PG8_BAR __builtin_amdgcn_s_barrier()
; #define PG8_SCHED __builtin_amdgcn_sched_barrier(0)
; template <class Epi, class Sched, bool ALIGN_EPI = false, bool SP2 = false>
; __device__ __forceinline__ void gemm_phase(PG8_LAS unsigned char* lds, const Gemm g, const Sched& S, const Epi& E) {
;     ...
;             PG8_WAIT_V(8); PG8_WAIT_L(0); PG8_BAR; PG8_MMA(1, 0, At, B0); PG8_MMA(1, 1, At, B1); PG8_BAR; PG8_SCHED;
;             PG8_LDB(B0, 1, 0); PG8_LDB(B1, 1, 1); PG8_SCHED; PG8_LDA(At, 1, 0); PG8_STAGE(PG8_SA(0, 1), a2 + hstep, voffA);
;             PG8_WAIT_V(8); PG8_WAIT_L(0); PG8_BAR; PG8_MMA(0, 0, At, B0); PG8_MMA(0, 1, At, B1); PG8_BAR; PG8_SCHED;
.Lrj7:
	s_waitcnt lgkmcnt(0)
	s_barrier
	v_mfma_f32_16x16x32_bf16 v[62:65], v[146:149], v[186:189], v[62:65]
	v_mfma_f32_16x16x32_bf16 v[58:61], v[162:165], v[186:189], v[58:61]
	v_mfma_f32_16x16x32_bf16 v[46:49], v[146:149], v[194:197], v[46:49]
	v_mfma_f32_16x16x32_bf16 v[42:45], v[162:165], v[194:197], v[42:45]
	v_mfma_f32_16x16x32_bf16 v[30:33], v[146:149], v[202:205], v[30:33]
	v_mfma_f32_16x16x32_bf16 v[26:29], v[162:165], v[202:205], v[26:29]
	v_mfma_f32_16x16x32_bf16 v[14:17], v[146:149], v[210:213], v[14:17]
	v_mfma_f32_16x16x32_bf16 v[10:13], v[162:165], v[210:213], v[10:13]
	v_mfma_f32_16x16x32_bf16 v[62:65], v[158:161], v[190:193], v[62:65]
	v_mfma_f32_16x16x32_bf16 v[58:61], v[166:169], v[190:193], v[58:61]
	v_mfma_f32_16x16x32_bf16 v[46:49], v[158:161], v[198:201], v[46:49]
	v_mfma_f32_16x16x32_bf16 v[42:45], v[166:169], v[198:201], v[42:45]
	v_mfma_f32_16x16x32_bf16 v[30:33], v[158:161], v[206:209], v[30:33]
	v_mfma_f32_16x16x32_bf16 v[26:29], v[166:169], v[206:209], v[26:29]
	v_mfma_f32_16x16x32_bf16 v[14:17], v[158:161], v[214:217], v[14:17]
	v_mfma_f32_16x16x32_bf16 v[10:13], v[166:169], v[214:217], v[10:13]
	v_mfma_f32_16x16x32_bf16 v[54:57], v[170:173], v[186:189], v[54:57]
	v_mfma_f32_16x16x32_bf16 v[50:53], v[178:181], v[186:189], v[50:53]
	v_mfma_f32_16x16x32_bf16 v[38:41], v[170:173], v[194:197], v[38:41]
	v_mfma_f32_16x16x32_bf16 v[34:37], v[178:181], v[194:197], v[34:37]
	v_mfma_f32_16x16x32_bf16 v[22:25], v[170:173], v[202:205], v[22:25]
	v_mfma_f32_16x16x32_bf16 v[18:21], v[178:181], v[202:205], v[18:21]
	v_mfma_f32_16x16x32_bf16 v[6:9], v[170:173], v[210:213], v[6:9]
	v_mfma_f32_16x16x32_bf16 v[2:5], v[178:181], v[210:213], v[2:5]
	v_mfma_f32_16x16x32_bf16 v[54:57], v[174:177], v[190:193], v[54:57]
	v_mfma_f32_16x16x32_bf16 v[50:53], v[182:185], v[190:193], v[50:53]
	v_mfma_f32_16x16x32_bf16 v[38:41], v[174:177], v[198:201], v[38:41]
	v_mfma_f32_16x16x32_bf16 v[34:37], v[182:185], v[198:201], v[34:37]
	v_mfma_f32_16x16x32_bf16 v[22:25], v[174:177], v[206:209], v[22:25]
	v_mfma_f32_16x16x32_bf16 v[18:21], v[182:185], v[206:209], v[18:21]
	v_mfma_f32_16x16x32_bf16 v[6:9], v[174:177], v[214:217], v[6:9]
	v_mfma_f32_16x16x32_bf16 v[2:5], v[182:185], v[214:217], v[2:5]
	s_barrier
	s_add_i32 s62, 0, 0x18000
	v_add_u32_e32 v157, s62, v152
	s_add_i32 s63, 0, 0x1c000
	ds_read_b128 v[146:149], v157
	ds_read_b128 v[158:161], v157 offset:1024
	ds_read_b128 v[162:165], v157 offset:2048
	ds_read_b128 v[166:169], v157 offset:3072
	v_add_u32_e32 v157, s63, v152
	ds_read_b128 v[170:173], v157
	ds_read_b128 v[174:177], v157 offset:1024
	ds_read_b128 v[178:181], v157 offset:2048
	ds_read_b128 v[182:185], v157 offset:3072
	s_add_u32 s42, s42, 0x40000
	s_addc_u32 s43, s43, 0
	s_mov_b32 m0, s44
	v_lshl_add_u64 v[224:225], s[42:43], 0, v[130:131]
	ds_read_b128 v[186:189], v156 offset:32768
	ds_read_b128 v[190:193], v156 offset:33792
	ds_read_b128 v[194:197], v156 offset:34816
	ds_read_b128 v[198:201], v156 offset:35840
	ds_read_b128 v[202:205], v156 offset:36864
	ds_read_b128 v[206:209], v156 offset:37888
	ds_read_b128 v[210:213], v156 offset:38912
	ds_read_b128 v[214:217], v156 offset:39936
	global_load_lds_dwordx4 v[224:225], off
	v_lshl_add_u64 v[224:225], s[42:43], 0, v[134:135]
	s_mov_b32 m0, s45
	s_nop 0
	global_load_lds_dwordx4 v[224:225], off
	s_waitcnt vmcnt(8)
	s_waitcnt lgkmcnt(0)
	s_barrier
	v_mfma_f32_16x16x32_bf16 v[126:129], v[146:149], v[186:189], v[126:129]
	v_mfma_f32_16x16x32_bf16 v[122:125], v[162:165], v[186:189], v[122:125]
	v_mfma_f32_16x16x32_bf16 v[110:113], v[146:149], v[194:197], v[110:113]
	v_mfma_f32_16x16x32_bf16 v[106:109], v[162:165], v[194:197], v[106:109]
	v_mfma_f32_16x16x32_bf16 v[94:97], v[146:149], v[202:205], v[94:97]
	v_mfma_f32_16x16x32_bf16 v[90:93], v[162:165], v[202:205], v[90:93]
	v_mfma_f32_16x16x32_bf16 v[78:81], v[146:149], v[210:213], v[78:81]
	v_mfma_f32_16x16x32_bf16 v[74:77], v[162:165], v[210:213], v[74:77]
	v_mfma_f32_16x16x32_bf16 v[126:129], v[158:161], v[190:193], v[126:129]
	v_mfma_f32_16x16x32_bf16 v[122:125], v[166:169], v[190:193], v[122:125]
	v_mfma_f32_16x16x32_bf16 v[110:113], v[158:161], v[198:201], v[110:113]
	v_mfma_f32_16x16x32_bf16 v[106:109], v[166:169], v[198:201], v[106:109]
	v_mfma_f32_16x16x32_bf16 v[94:97], v[158:161], v[206:209], v[94:97]
	v_mfma_f32_16x16x32_bf16 v[90:93], v[166:169], v[206:209], v[90:93]
	v_mfma_f32_16x16x32_bf16 v[78:81], v[158:161], v[214:217], v[78:81]
	v_mfma_f32_16x16x32_bf16 v[74:77], v[166:169], v[214:217], v[74:77]
	v_mfma_f32_16x16x32_bf16 v[118:121], v[170:173], v[186:189], v[118:121]
	v_mfma_f32_16x16x32_bf16 v[114:117], v[178:181], v[186:189], v[114:117]
	v_mfma_f32_16x16x32_bf16 v[102:105], v[170:173], v[194:197], v[102:105]
	v_mfma_f32_16x16x32_bf16 v[98:101], v[178:181], v[194:197], v[98:101]
	v_mfma_f32_16x16x32_bf16 v[86:89], v[170:173], v[202:205], v[86:89]
	v_mfma_f32_16x16x32_bf16 v[82:85], v[178:181], v[202:205], v[82:85]
	v_mfma_f32_16x16x32_bf16 v[70:73], v[170:173], v[210:213], v[70:73]
	v_mfma_f32_16x16x32_bf16 v[66:69], v[178:181], v[210:213], v[66:69]
	v_mfma_f32_16x16x32_bf16 v[118:121], v[174:177], v[190:193], v[118:121]
	v_mfma_f32_16x16x32_bf16 v[114:117], v[182:185], v[190:193], v[114:117]
	v_mfma_f32_16x16x32_bf16 v[102:105], v[174:177], v[198:201], v[102:105]
	v_mfma_f32_16x16x32_bf16 v[98:101], v[182:185], v[198:201], v[98:101]
	v_mfma_f32_16x16x32_bf16 v[86:89], v[174:177], v[206:209], v[86:89]
	v_mfma_f32_16x16x32_bf16 v[82:85], v[182:185], v[206:209], v[82:85]
	v_mfma_f32_16x16x32_bf16 v[70:73], v[174:177], v[214:217], v[70:73]
	v_mfma_f32_16x16x32_bf16 v[66:69], v[182:185], v[214:217], v[66:69]
	s_barrier
;     __device__ __forceinline__ void operator()(const f32x4 (&acc)[2][2][4][2], const Unit& u, int wr, int wc, int fr, int fq) const {
;     ...
;         for (int ai = 0; ai < 2; ++ai)
; #pragma unroll
;             for (int m = 0; m < 4; ++m) { bf16_t* rowp = O + (size_t)(row0 + ai * HALF + m * 16) * ldc + col0;
; #pragma unroll
;                 for (int bj = 0; bj < 2; ++bj) { f32x4 v0 = acc[ai][bj][m][0], v1 = acc[ai][bj][m][1];
;                     if (ROWSCALE) { v0 = v0 * rs[ai][m]; v1 = v1 * rs[ai][m]; }
;                     if (ACT == 2) {
; #pragma unroll
; template <class Epi, class Sched, bool ALIGN_EPI = false, bool SP2 = false>
; __device__ __forceinline__ void gemm_phase(PG8_LAS unsigned char* lds, const Gemm g, const Sched& S, const Epi& E) {
;     ...
;             PG8_LDA(At, 1, 1); PG8_STAGE(PG8_SB(1, 0), b3, voffB); PG8_STAGE(PG8_SB(1, 1), b3 + hstepB, voffB); PG8_STAGE(PG8_SA(1, 0), a3, voffA);
;             PG8_WAIT_V(8); PG8_WAIT_L(0); PG8_BAR; PG8_MMA(1, 0, At, B0); PG8_MMA(1, 1, At, B1); PG8_BAR; PG8_SCHED;
;             } else {
;             PG8_LDB(B0, 0, 0); PG8_SCHED; PG8_LDA(At, 0, 0); PG8_STAGE(PG8_SA(1, 1), a1 + hstep, voffA);
;             PG8_WAIT_L(8); PG8_BAR; PG8_WAIT_L(0); PG8_MMA(0, 0, At, B0); PG8_BAR; PG8_SCHED;
;             PG8_LDB(B1, 0, 1); PG8_STAGE(PG8_SB(0, 0), b2, voffB);
;             PG8_BAR; PG8_WAIT_L(0); PG8_MMA(0, 1, At, B1); PG8_BAR;
;             PG8_LDA(At, 0, 1); PG8_STAGE(PG8_SA(0, 0), a2, voffA);
;             PG8_BAR; PG8_WAIT_L(0); PG8_MMA(1, 0, At, B0); PG8_BAR; PG8_SCHED;
;             PG8_STAGE(PG8_SB(0, 1), b2 + hstepB, voffB);
;             PG8_WAIT_V(6); PG8_BAR; PG8_MMA(1, 1, At, B1); PG8_BAR;
;             PG8_LDB(B0, 1, 0); PG8_SCHED; PG8_LDA(At, 1, 0); PG8_STAGE(PG8_SA(0, 1), a2 + hstep, voffA);
;             PG8_WAIT_L(8); PG8_BAR; PG8_WAIT_L(0); PG8_MMA(0, 0, At, B0); PG8_BAR; PG8_SCHED;
;             PG8_LDB(B1, 1, 1); PG8_STAGE(PG8_SB(1, 0), b3, voffB);
;             PG8_BAR; PG8_WAIT_L(0); PG8_MMA(0, 1, At, B1); PG8_BAR;
;             PG8_LDA(At, 1, 1); PG8_STAGE(PG8_SA(1, 0), a3, voffA);
;             PG8_BAR; PG8_WAIT_L(0); PG8_MMA(1, 0, At, B0); PG8_BAR; PG8_SCHED;
;             PG8_STAGE(PG8_SB(1, 1), b3 + hstepB, voffB);
;             PG8_WAIT_V(6); PG8_BAR; PG8_MMA(1, 1, At, B1); PG8_BAR;
;             }
;         }
;         if constexpr (ALIGN_EPI) { if (wr == 0) PG8_BAR; }
	s_add_i32 s42, s62, s30
	v_lshl_add_u64 v[150:151], v[150:151], 0, s[10:11]
	s_mov_b32 m0, s42
	ds_read_b128 v[186:189], v156 offset:49152
	ds_read_b128 v[190:193], v156 offset:50176
	ds_read_b128 v[194:197], v156 offset:51200
	ds_read_b128 v[198:201], v156 offset:52224
	ds_read_b128 v[202:205], v156 offset:53248
	ds_read_b128 v[206:209], v156 offset:54272
	ds_read_b128 v[210:213], v156 offset:55296
	ds_read_b128 v[214:217], v156 offset:56320
	global_load_lds_dwordx4 v[150:151], off
	s_add_i32 m0, s42, 0x2000
	s_add_u32 s40, s40, 0x10080
	v_lshl_add_u64 v[150:151], v[218:219], 0, s[10:11]
	s_addc_u32 s41, s41, 0
	s_add_i32 s42, s63, s30
	global_load_lds_dwordx4 v[150:151], off
	v_lshl_add_u64 v[150:151], s[40:41], 0, v[132:133]
	s_mov_b32 m0, s42
	s_nop 0
	global_load_lds_dwordx4 v[150:151], off
	v_lshl_add_u64 v[150:151], s[40:41], 0, v[136:137]
	s_add_i32 m0, s42, 0x2000
	s_nop 0
	global_load_lds_dwordx4 v[150:151], off
	v_lshl_add_u64 v[150:151], v[220:221], 0, s[10:11]
	s_mov_b32 m0, s47
	s_nop 0
	global_load_lds_dwordx4 v[150:151], off
	v_lshl_add_u64 v[150:151], v[222:223], 0, s[10:11]
	s_mov_b32 m0, s54
	s_nop 0
	global_load_lds_dwordx4 v[150:151], off
	s_waitcnt vmcnt(8)
	s_waitcnt lgkmcnt(0)
	s_barrier
	v_mfma_f32_16x16x32_bf16 v[62:65], v[146:149], v[186:189], v[62:65]
	v_mfma_f32_16x16x32_bf16 v[58:61], v[162:165], v[186:189], v[58:61]
	v_mfma_f32_16x16x32_bf16 v[46:49], v[146:149], v[194:197], v[46:49]
	v_mfma_f32_16x16x32_bf16 v[42:45], v[162:165], v[194:197], v[42:45]
	v_mfma_f32_16x16x32_bf16 v[30:33], v[146:149], v[202:205], v[30:33]
	v_mfma_f32_16x16x32_bf16 v[26:29], v[162:165], v[202:205], v[26:29]
	v_mfma_f32_16x16x32_bf16 v[14:17], v[146:149], v[210:213], v[14:17]
	v_mfma_f32_16x16x32_bf16 v[10:13], v[162:165], v[210:213], v[10:13]
	v_mfma_f32_16x16x32_bf16 v[62:65], v[158:161], v[190:193], v[62:65]
	v_mfma_f32_16x16x32_bf16 v[58:61], v[166:169], v[190:193], v[58:61]
	v_mfma_f32_16x16x32_bf16 v[46:49], v[158:161], v[198:201], v[46:49]
	v_mfma_f32_16x16x32_bf16 v[42:45], v[166:169], v[198:201], v[42:45]
	v_mfma_f32_16x16x32_bf16 v[30:33], v[158:161], v[206:209], v[30:33]
	v_mfma_f32_16x16x32_bf16 v[26:29], v[166:169], v[206:209], v[26:29]
	v_mfma_f32_16x16x32_bf16 v[14:17], v[158:161], v[214:217], v[14:17]
	v_mfma_f32_16x16x32_bf16 v[10:13], v[166:169], v[214:217], v[10:13]
	v_mfma_f32_16x16x32_bf16 v[54:57], v[170:173], v[186:189], v[54:57]
	v_mfma_f32_16x16x32_bf16 v[50:53], v[178:181], v[186:189], v[50:53]
	v_mfma_f32_16x16x32_bf16 v[38:41], v[170:173], v[194:197], v[38:41]
	v_mfma_f32_16x16x32_bf16 v[34:37], v[178:181], v[194:197], v[34:37]
	v_mfma_f32_16x16x32_bf16 v[22:25], v[170:173], v[202:205], v[22:25]
	v_mfma_f32_16x16x32_bf16 v[18:21], v[178:181], v[202:205], v[18:21]
	v_mfma_f32_16x16x32_bf16 v[6:9], v[170:173], v[210:213], v[6:9]
	v_mfma_f32_16x16x32_bf16 v[2:5], v[178:181], v[210:213], v[2:5]
	v_mfma_f32_16x16x32_bf16 v[54:57], v[174:177], v[190:193], v[54:57]
	v_mfma_f32_16x16x32_bf16 v[50:53], v[182:185], v[190:193], v[50:53]
	v_mfma_f32_16x16x32_bf16 v[38:41], v[174:177], v[198:201], v[38:41]
	v_mfma_f32_16x16x32_bf16 v[34:37], v[182:185], v[198:201], v[34:37]
	v_mfma_f32_16x16x32_bf16 v[22:25], v[174:177], v[206:209], v[22:25]
	v_mfma_f32_16x16x32_bf16 v[18:21], v[182:185], v[206:209], v[18:21]
	v_mfma_f32_16x16x32_bf16 v[6:9], v[174:177], v[214:217], v[6:9]
	v_mfma_f32_16x16x32_bf16 v[2:5], v[182:185], v[214:217], v[2:5]
	s_barrier
	s_add_i32 s61, s61, 2
	s_add_u32 s38, s38, 0x100
	s_addc_u32 s39, s39, 0
	s_add_u32 s59, s59, 0x100
	s_addc_u32 s60, s60, 0
	s_cmp_gt_u32 s61, 13
	s_cbranch_scc0 .LBB0_1313
	s_and_b64 vcc, exec, s[14:15]
	s_cbranch_vccz .LBB0_1316
	s_barrier
.LBB0_1316:
	s_mov_b32 s101, 1
	v_lshl_add_u32 v148, s8, 8, v1
	v_max_f32_e32 v122, v122, v122
	v_max_f32_e32 v123, v123, v123
	v_max_f32_e32 v124, v124, v124
	v_ashrrev_i32_e32 v149, 31, v148
	v_max_f32_e32 v122, 0, v122
	v_max_f32_e32 v123, 0, v123
	v_max_f32_e32 v124, 0, v124
	v_lshl_or_b32 v146, s36, 8, v153
	v_lshlrev_b64 v[150:151], 13, v[148:149]
	v_mul_f32_e32 v157, v122, v122
	v_max_f32_e32 v122, v127, v127
	v_mul_f32_e32 v127, v123, v123
	v_max_f32_e32 v123, v128, v128
	v_mul_f32_e32 v128, v124, v124
	v_max_f32_e32 v124, v129, v129
	v_max_f32_e32 v125, v125, v125
	v_ashrrev_i32_e32 v147, 31, v146
	v_lshl_add_u64 v[150:151], s[52:53], 0, v[150:151]
	v_max_f32_e32 v126, v126, v126
	v_max_f32_e32 v122, 0, v122
	v_max_f32_e32 v123, 0, v123
	v_max_f32_e32 v124, 0, v124
	v_max_f32_e32 v125, 0, v125
	v_lshl_add_u64 v[150:151], v[146:147], 1, v[150:151]
	v_max_f32_e32 v126, 0, v126
	v_mul_f32_e32 v122, v122, v122
	v_mul_f32_e32 v123, v123, v123
	v_mul_f32_e32 v124, v124, v124
	v_mul_f32_e32 v125, v125, v125
	v_cmp_gt_i32_e32 vcc, 2.0, v146
	v_mul_f32_e32 v126, v126, v126
	v_cvt_pk_bf16_f32 v122, v126, v122
	v_cvt_pk_bf16_f32 v123, v123, v124
	v_cvt_pk_bf16_f32 v124, v157, v127
	v_cvt_pk_bf16_f32 v125, v128, v125
	s_and_saveexec_b64 s[8:9], vcc
	s_cbranch_execz .LBB0_1318
	global_store_dwordx4 v[150:151], v[122:125], off
